# grid barrier cross-XCD level hand-written: each XCD leader adds to every XCD's release word after its L2 writeback; release when word reaches (round+1)*nx (no returning cross-XCD atomic, no relay)
# baseline (speedup 1.0000x reference)
; __device__ __forceinline__ unsigned xb_ld(unsigned* p)              { return __hip_atomic_load(p, __ATOMIC_RELAXED, __HIP_MEMORY_SCOPE_AGENT); }
; __device__ __forceinline__ unsigned xb_add(unsigned* p, unsigned v) { return __hip_atomic_fetch_add(p, v, __ATOMIC_RELAXED, __HIP_MEMORY_SCOPE_AGENT); }
; #define XB_SPIN(cond, bar) do { unsigned _sp = 0; while (cond) { __builtin_amdgcn_s_sleep(1); \
;     if ((++_sp & 255u) == 0u) { if (xb_ld(&(bar)[XB_TMO])) break; if (_sp > XB_SPIN_CAP) { atomicAdd(&(bar)[XB_TMO], 1u); break; } } } } while (0)
; __device__ __forceinline__ void xcd_barrier(const XcdBarrier& b) {
;     ...
;         const unsigned old = xb_add(&bar[XB_XSUB(b.x)], 1u);
;         const unsigned gen = old / nloc;
;         if (old + 1u == (gen + 1u) * nloc) {
;             __builtin_amdgcn_fence(__ATOMIC_RELEASE, "agent");
;             asm volatile("s_waitcnt vmcnt(0)" ::: "memory");
;             const unsigned og = xb_add(&bar[XB_TOP], 1u);
;             const unsigned tg = og / nx;
;             if (og + 1u == (tg + 1u) * nx) xb_add(&bar[XB_TOPGEN], 1u);
;             else XB_SPIN(xb_ld(&bar[XB_TOPGEN]) == tg, bar);
.LBB0_1148:
	s_or_b64 exec, exec, s[2:3]
	v_cvt_f32_u32_e32 v4, v2
	s_waitcnt vmcnt(0)
	v_readfirstlane_b32 s2, v3
	v_sub_u32_e32 v3, 0, v2
	v_rcp_iflag_f32_e32 v4, v4
	v_add_u32_e32 v5, s2, v1
	v_mul_f32_e32 v4, 0x4f7ffffe, v4
	v_cvt_u32_f32_e32 v4, v4
	v_mul_lo_u32 v1, v3, v4
	v_mul_hi_u32 v1, v4, v1
	v_add_u32_e32 v1, v4, v1
	v_mul_hi_u32 v1, v5, v1
	v_mul_lo_u32 v3, v1, v2
	v_sub_u32_e32 v3, v5, v3
	v_add_u32_e32 v4, 1, v1
	v_cmp_ge_u32_e32 vcc, v3, v2
	s_nop 1
	v_cndmask_b32_e32 v1, v1, v4, vcc
	v_sub_u32_e32 v4, v3, v2
	v_cndmask_b32_e32 v3, v3, v4, vcc
	v_add_u32_e32 v4, 1, v1
	v_cmp_ge_u32_e32 vcc, v3, v2
	v_add_u32_e32 v3, 1, v5
	s_nop 0
	v_cndmask_b32_e32 v1, v1, v4, vcc
	v_mul_lo_u32 v4, v2, v1
	v_add_u32_e32 v2, v4, v2
	v_cmp_ne_u32_e32 vcc, v3, v2
	s_waitcnt lgkmcnt(0)
	v_add_u32_e32 v1, 1, v1
	v_mul_lo_u32 v1, v1, v0
	v_readlane_b32 s2, v254, 42
	v_readlane_b32 s3, v254, 43
	s_cbranch_vccnz .Lxb_wait
	buffer_wbl2 sc1
	s_waitcnt vmcnt(0)
	v_readlane_b32 s100, v254, 46
	v_readlane_b32 s101, v254, 47
	v_mov_b32_e32 v3, 1
	s_sub_u32 s100, s100, 0x1100
	s_subb_u32 s101, s101, 0
	s_nop 1

; __device__ __forceinline__ unsigned xb_ld(unsigned* p)              { return __hip_atomic_load(p, __ATOMIC_RELAXED, __HIP_MEMORY_SCOPE_AGENT); }
; __device__ __forceinline__ unsigned xb_add(unsigned* p, unsigned v) { return __hip_atomic_fetch_add(p, v, __ATOMIC_RELAXED, __HIP_MEMORY_SCOPE_AGENT); }
; #define XB_SPIN(cond, bar) do { unsigned _sp = 0; while (cond) { __builtin_amdgcn_s_sleep(1); \
;     if ((++_sp & 255u) == 0u) { if (xb_ld(&(bar)[XB_TMO])) break; if (_sp > XB_SPIN_CAP) { atomicAdd(&(bar)[XB_TMO], 1u); break; } } } } while (0)
; __device__ __forceinline__ void xcd_barrier(const XcdBarrier& b) {
;     ...
;             const unsigned og = xb_add(&bar[XB_TOP], 1u);
;             const unsigned tg = og / nx;
;             if (og + 1u == (tg + 1u) * nx) xb_add(&bar[XB_TOPGEN], 1u);
;             else XB_SPIN(xb_ld(&bar[XB_TOPGEN]) == tg, bar);
;             __builtin_amdgcn_fence(__ATOMIC_ACQUIRE, "agent");
;             xb_add(&bar[XB_XGEN(b.x)], 1u);
;             asm volatile("s_waitcnt vmcnt(0)" ::: "memory");
;         } else {
;             XB_SPIN(xb_ld(&bar[XB_XGEN(b.x)]) == gen, bar);
;             __builtin_amdgcn_fence(__ATOMIC_ACQUIRE, "agent");
;             asm volatile("s_waitcnt vmcnt(0)" ::: "memory");
	global_atomic_add v181, v3, s[100:101]
	global_atomic_add v181, v3, s[100:101] offset:256
	global_atomic_add v181, v3, s[100:101] offset:512
	global_atomic_add v181, v3, s[100:101] offset:768
	global_atomic_add v181, v3, s[100:101] offset:1024
	global_atomic_add v181, v3, s[100:101] offset:1280
	global_atomic_add v181, v3, s[100:101] offset:1536
	global_atomic_add v181, v3, s[100:101] offset:1792
	global_atomic_add v181, v3, s[100:101] offset:2048
	global_atomic_add v181, v3, s[100:101] offset:2304
	global_atomic_add v181, v3, s[100:101] offset:2560
	global_atomic_add v181, v3, s[100:101] offset:2816
	global_atomic_add v181, v3, s[100:101] offset:3072
	global_atomic_add v181, v3, s[100:101] offset:3328
	global_atomic_add v181, v3, s[100:101] offset:3584
	global_atomic_add v181, v3, s[100:101] offset:3840
.Lxb_wait:
	s_mov_b32 s4, 0
	s_nop 3
.Lxb_spin:
	global_load_dword v0, v181, s[2:3] sc1
	s_waitcnt vmcnt(0)
	v_cmp_le_u32_e32 vcc, v1, v0
	s_cbranch_vccnz .Lxb_done
	s_sleep 1
	s_add_u32 s4, s4, 1
	s_and_b32 s5, s4, 0xff
	s_cmp_lg_u32 s5, 0
	s_cbranch_scc1 .Lxb_spin
	global_load_dword v0, v181, s[84:85] sc1
	s_waitcnt vmcnt(0)
	v_cmp_ne_u32_e32 vcc, 0, v0
	s_cbranch_vccnz .Lxb_done
	s_cmp_lt_u32 s4, 0x40001
	s_cbranch_scc1 .Lxb_spin
	global_atomic_add v181, v203, s[84:85]
.Lxb_done:
	s_waitcnt vmcnt(0)
	buffer_inv sc1
	s_waitcnt vmcnt(0)
	s_branch .LBB0_17

